# static s_setprio raise for waves 0-3 (mirror variant) in all GEMM K loops
# baseline (speedup 1.0000x reference)
.LBB0_276:
	s_and_b64 s[30:31], s[20:21], exec
	s_cselect_b32 s2, s17, s27
	s_cselect_b32 s13, s16, s26
	s_cselect_b32 s15, s19, s29
	s_cselect_b32 s23, s18, s28
	s_add_u32 s26, s26, 0x80080
	s_addc_u32 s27, s27, 0
	s_add_u32 s25, s28, 0x100
	v_mov_b32_e32 v2, 0
	s_addc_u32 s33, s29, 0
	s_mov_b32 s50, -2
	v_mov_b32_e32 v3, v2
	v_mov_b32_e32 v4, v2
	v_mov_b32_e32 v5, v2
	v_mov_b32_e32 v6, v2
	v_mov_b32_e32 v7, v2
	v_mov_b32_e32 v8, v2
	v_mov_b32_e32 v9, v2
	v_mov_b32_e32 v18, v2
	v_mov_b32_e32 v19, v2
	v_mov_b32_e32 v20, v2
	v_mov_b32_e32 v21, v2
	v_mov_b32_e32 v22, v2
	v_mov_b32_e32 v23, v2
	v_mov_b32_e32 v24, v2
	v_mov_b32_e32 v25, v2
	v_mov_b32_e32 v34, v2
	v_mov_b32_e32 v35, v2
	v_mov_b32_e32 v36, v2
	v_mov_b32_e32 v37, v2
	v_mov_b32_e32 v38, v2
	v_mov_b32_e32 v39, v2
	v_mov_b32_e32 v40, v2
	v_mov_b32_e32 v41, v2
	v_mov_b32_e32 v50, v2
	v_mov_b32_e32 v51, v2
	v_mov_b32_e32 v52, v2
	v_mov_b32_e32 v53, v2
	v_mov_b32_e32 v54, v2
	v_mov_b32_e32 v55, v2
	v_mov_b32_e32 v56, v2
	v_mov_b32_e32 v57, v2
	v_mov_b32_e32 v10, v2
	v_mov_b32_e32 v11, v2
	v_mov_b32_e32 v12, v2
	v_mov_b32_e32 v13, v2
	v_mov_b32_e32 v14, v2
	v_mov_b32_e32 v15, v2
	v_mov_b32_e32 v16, v2
	v_mov_b32_e32 v17, v2
	v_mov_b32_e32 v26, v2
	v_mov_b32_e32 v27, v2
	v_mov_b32_e32 v28, v2
	v_mov_b32_e32 v29, v2
	v_mov_b32_e32 v30, v2
	v_mov_b32_e32 v31, v2
	v_mov_b32_e32 v32, v2
	v_mov_b32_e32 v33, v2
	v_mov_b32_e32 v42, v2
	v_mov_b32_e32 v43, v2
	v_mov_b32_e32 v44, v2
	v_mov_b32_e32 v45, v2
	v_mov_b32_e32 v46, v2
	v_mov_b32_e32 v47, v2
	v_mov_b32_e32 v48, v2
	v_mov_b32_e32 v49, v2
	v_mov_b32_e32 v58, v2
	v_mov_b32_e32 v59, v2
	v_mov_b32_e32 v60, v2
	v_mov_b32_e32 v61, v2
	v_mov_b32_e32 v62, v2
	v_mov_b32_e32 v63, v2
	v_mov_b32_e32 v64, v2
	v_mov_b32_e32 v65, v2
	v_mov_b32_e32 v66, v2
	v_mov_b32_e32 v67, v2
	v_mov_b32_e32 v68, v2
	v_mov_b32_e32 v69, v2
	v_mov_b32_e32 v70, v2
	v_mov_b32_e32 v71, v2
	v_mov_b32_e32 v72, v2
	v_mov_b32_e32 v73, v2
	v_mov_b32_e32 v82, v2
	v_mov_b32_e32 v83, v2
	v_mov_b32_e32 v84, v2
	v_mov_b32_e32 v85, v2
	v_mov_b32_e32 v86, v2
	v_mov_b32_e32 v87, v2
	v_mov_b32_e32 v88, v2
	v_mov_b32_e32 v89, v2
	v_mov_b32_e32 v98, v2
	v_mov_b32_e32 v99, v2
	v_mov_b32_e32 v100, v2
	v_mov_b32_e32 v101, v2
	v_mov_b32_e32 v102, v2
	v_mov_b32_e32 v103, v2
	v_mov_b32_e32 v104, v2
	v_mov_b32_e32 v105, v2
	v_mov_b32_e32 v114, v2
	v_mov_b32_e32 v115, v2
	v_mov_b32_e32 v116, v2
	v_mov_b32_e32 v117, v2
	v_mov_b32_e32 v118, v2
	v_mov_b32_e32 v119, v2
	v_mov_b32_e32 v120, v2
	v_mov_b32_e32 v121, v2
	v_mov_b32_e32 v74, v2
	v_mov_b32_e32 v75, v2
	v_mov_b32_e32 v76, v2
	v_mov_b32_e32 v77, v2
	v_mov_b32_e32 v78, v2
	v_mov_b32_e32 v79, v2
	v_mov_b32_e32 v80, v2
	v_mov_b32_e32 v81, v2
	v_mov_b32_e32 v90, v2
	v_mov_b32_e32 v91, v2
	v_mov_b32_e32 v92, v2
	v_mov_b32_e32 v93, v2
	v_mov_b32_e32 v94, v2
	v_mov_b32_e32 v95, v2
	v_mov_b32_e32 v96, v2
	v_mov_b32_e32 v97, v2
	v_mov_b32_e32 v106, v2
	v_mov_b32_e32 v107, v2
	v_mov_b32_e32 v108, v2
	v_mov_b32_e32 v109, v2
	v_mov_b32_e32 v110, v2
	v_mov_b32_e32 v111, v2
	v_mov_b32_e32 v112, v2
	v_mov_b32_e32 v113, v2
	v_mov_b32_e32 v122, v2
	v_mov_b32_e32 v123, v2
	v_mov_b32_e32 v124, v2
	v_mov_b32_e32 v125, v2
	v_mov_b32_e32 v126, v2
	v_mov_b32_e32 v127, v2
	v_mov_b32_e32 v128, v2
	v_mov_b32_e32 v129, v2
	s_and_b64 vcc, exec, s[6:7]
	s_cbranch_vccnz .Lsp_p1
	s_setprio 1

.LBB0_703:
	s_add_u32 s22, s22, 0x80080
	s_addc_u32 s23, s23, 0
	s_add_u32 s5, s24, 0x100
	v_mov_b32_e32 v2, 0
	s_addc_u32 s15, s25, 0
	s_mov_b32 s45, -2
	v_mov_b32_e32 v3, v2
	v_mov_b32_e32 v4, v2
	v_mov_b32_e32 v5, v2
	v_mov_b32_e32 v6, v2
	v_mov_b32_e32 v7, v2
	v_mov_b32_e32 v8, v2
	v_mov_b32_e32 v9, v2
	v_mov_b32_e32 v18, v2
	v_mov_b32_e32 v19, v2
	v_mov_b32_e32 v20, v2
	v_mov_b32_e32 v21, v2
	v_mov_b32_e32 v22, v2
	v_mov_b32_e32 v23, v2
	v_mov_b32_e32 v24, v2
	v_mov_b32_e32 v25, v2
	v_mov_b32_e32 v34, v2
	v_mov_b32_e32 v35, v2
	v_mov_b32_e32 v36, v2
	v_mov_b32_e32 v37, v2
	v_mov_b32_e32 v38, v2
	v_mov_b32_e32 v39, v2
	v_mov_b32_e32 v40, v2
	v_mov_b32_e32 v41, v2
	v_mov_b32_e32 v50, v2
	v_mov_b32_e32 v51, v2
	v_mov_b32_e32 v52, v2
	v_mov_b32_e32 v53, v2
	v_mov_b32_e32 v54, v2
	v_mov_b32_e32 v55, v2
	v_mov_b32_e32 v56, v2
	v_mov_b32_e32 v57, v2
	v_mov_b32_e32 v10, v2
	v_mov_b32_e32 v11, v2
	v_mov_b32_e32 v12, v2
	v_mov_b32_e32 v13, v2
	v_mov_b32_e32 v14, v2
	v_mov_b32_e32 v15, v2
	v_mov_b32_e32 v16, v2
	v_mov_b32_e32 v17, v2
	v_mov_b32_e32 v26, v2
	v_mov_b32_e32 v27, v2
	v_mov_b32_e32 v28, v2
	v_mov_b32_e32 v29, v2
	v_mov_b32_e32 v30, v2
	v_mov_b32_e32 v31, v2
	v_mov_b32_e32 v32, v2
	v_mov_b32_e32 v33, v2
	v_mov_b32_e32 v42, v2
	v_mov_b32_e32 v43, v2
	v_mov_b32_e32 v44, v2
	v_mov_b32_e32 v45, v2
	v_mov_b32_e32 v46, v2
	v_mov_b32_e32 v47, v2
	v_mov_b32_e32 v48, v2
	v_mov_b32_e32 v49, v2
	v_mov_b32_e32 v58, v2
	v_mov_b32_e32 v59, v2
	v_mov_b32_e32 v60, v2
	v_mov_b32_e32 v61, v2
	v_mov_b32_e32 v62, v2
	v_mov_b32_e32 v63, v2
	v_mov_b32_e32 v64, v2
	v_mov_b32_e32 v65, v2
	v_mov_b32_e32 v66, v2
	v_mov_b32_e32 v67, v2
	v_mov_b32_e32 v68, v2
	v_mov_b32_e32 v69, v2
	v_mov_b32_e32 v70, v2
	v_mov_b32_e32 v71, v2
	v_mov_b32_e32 v72, v2
	v_mov_b32_e32 v73, v2
	v_mov_b32_e32 v82, v2
	v_mov_b32_e32 v83, v2
	v_mov_b32_e32 v84, v2
	v_mov_b32_e32 v85, v2
	v_mov_b32_e32 v86, v2
	v_mov_b32_e32 v87, v2
	v_mov_b32_e32 v88, v2
	v_mov_b32_e32 v89, v2
	v_mov_b32_e32 v98, v2
	v_mov_b32_e32 v99, v2
	v_mov_b32_e32 v100, v2
	v_mov_b32_e32 v101, v2
	v_mov_b32_e32 v102, v2
	v_mov_b32_e32 v103, v2
	v_mov_b32_e32 v104, v2
	v_mov_b32_e32 v105, v2
	v_mov_b32_e32 v114, v2
	v_mov_b32_e32 v115, v2
	v_mov_b32_e32 v116, v2
	v_mov_b32_e32 v117, v2
	v_mov_b32_e32 v118, v2
	v_mov_b32_e32 v119, v2
	v_mov_b32_e32 v120, v2
	v_mov_b32_e32 v121, v2
	v_mov_b32_e32 v74, v2
	v_mov_b32_e32 v75, v2
	v_mov_b32_e32 v76, v2
	v_mov_b32_e32 v77, v2
	v_mov_b32_e32 v78, v2
	v_mov_b32_e32 v79, v2
	v_mov_b32_e32 v80, v2
	v_mov_b32_e32 v81, v2
	v_mov_b32_e32 v90, v2
	v_mov_b32_e32 v91, v2
	v_mov_b32_e32 v92, v2
	v_mov_b32_e32 v93, v2
	v_mov_b32_e32 v94, v2
	v_mov_b32_e32 v95, v2
	v_mov_b32_e32 v96, v2
	v_mov_b32_e32 v97, v2
	v_mov_b32_e32 v106, v2
	v_mov_b32_e32 v107, v2
	v_mov_b32_e32 v108, v2
	v_mov_b32_e32 v109, v2
	v_mov_b32_e32 v110, v2
	v_mov_b32_e32 v111, v2
	v_mov_b32_e32 v112, v2
	v_mov_b32_e32 v113, v2
	v_mov_b32_e32 v122, v2
	v_mov_b32_e32 v123, v2
	v_mov_b32_e32 v124, v2
	v_mov_b32_e32 v125, v2
	v_mov_b32_e32 v126, v2
	v_mov_b32_e32 v127, v2
	v_mov_b32_e32 v128, v2
	v_mov_b32_e32 v129, v2
	s_and_b64 s[98:99], exec, s[12:13]
	s_cbranch_scc0 .Lsp_p4
	s_setprio 1

.LBB0_841:
	s_add_i32 s46, s45, -2
	s_add_u32 s4, s4, 0x60080
	s_addc_u32 s5, s5, 0
	s_add_u32 s47, s20, 0x100
	s_addc_u32 s48, s21, 0
	s_mov_b32 s20, 0
	s_and_b64 s[98:99], exec, s[10:11]
	s_cbranch_scc0 .Lsp_p5
	s_setprio 1

.LBB0_1018:
	s_and_b64 s[30:31], s[22:23], exec
	s_cselect_b32 s1, s19, s27
	s_cselect_b32 s15, s18, s26
	s_cselect_b32 s17, s21, s29
	s_cselect_b32 s46, s20, s28
	s_add_u32 s26, s26, 0x80080
	s_addc_u32 s27, s27, 0
	s_add_u32 s47, s28, 0x100
	v_mov_b32_e32 v2, 0
	s_addc_u32 s48, s29, 0
	s_mov_b32 s49, -2
	s_waitcnt lgkmcnt(0)
	v_mov_b32_e32 v3, v2
	v_mov_b32_e32 v4, v2
	v_mov_b32_e32 v5, v2
	v_mov_b32_e32 v6, v2
	v_mov_b32_e32 v7, v2
	v_mov_b32_e32 v8, v2
	v_mov_b32_e32 v9, v2
	v_mov_b32_e32 v18, v2
	v_mov_b32_e32 v19, v2
	v_mov_b32_e32 v20, v2
	v_mov_b32_e32 v21, v2
	v_mov_b32_e32 v22, v2
	v_mov_b32_e32 v23, v2
	v_mov_b32_e32 v24, v2
	v_mov_b32_e32 v25, v2
	v_mov_b32_e32 v34, v2
	v_mov_b32_e32 v35, v2
	v_mov_b32_e32 v36, v2
	v_mov_b32_e32 v37, v2
	v_mov_b32_e32 v38, v2
	v_mov_b32_e32 v39, v2
	v_mov_b32_e32 v40, v2
	v_mov_b32_e32 v41, v2
	v_mov_b32_e32 v50, v2
	v_mov_b32_e32 v51, v2
	v_mov_b32_e32 v52, v2
	v_mov_b32_e32 v53, v2
	v_mov_b32_e32 v54, v2
	v_mov_b32_e32 v55, v2
	v_mov_b32_e32 v56, v2
	v_mov_b32_e32 v57, v2
	v_mov_b32_e32 v10, v2
	v_mov_b32_e32 v11, v2
	v_mov_b32_e32 v12, v2
	v_mov_b32_e32 v13, v2
	v_mov_b32_e32 v14, v2
	v_mov_b32_e32 v15, v2
	v_mov_b32_e32 v16, v2
	v_mov_b32_e32 v17, v2
	v_mov_b32_e32 v26, v2
	v_mov_b32_e32 v27, v2
	v_mov_b32_e32 v28, v2
	v_mov_b32_e32 v29, v2
	v_mov_b32_e32 v30, v2
	v_mov_b32_e32 v31, v2
	v_mov_b32_e32 v32, v2
	v_mov_b32_e32 v33, v2
	v_mov_b32_e32 v42, v2
	v_mov_b32_e32 v43, v2
	v_mov_b32_e32 v44, v2
	v_mov_b32_e32 v45, v2
	v_mov_b32_e32 v46, v2
	v_mov_b32_e32 v47, v2
	v_mov_b32_e32 v48, v2
	v_mov_b32_e32 v49, v2
	v_mov_b32_e32 v58, v2
	v_mov_b32_e32 v59, v2
	v_mov_b32_e32 v60, v2
	v_mov_b32_e32 v61, v2
	v_mov_b32_e32 v62, v2
	v_mov_b32_e32 v63, v2
	v_mov_b32_e32 v64, v2
	v_mov_b32_e32 v65, v2
	v_mov_b32_e32 v66, v2
	v_mov_b32_e32 v67, v2
	v_mov_b32_e32 v68, v2
	v_mov_b32_e32 v69, v2
	v_mov_b32_e32 v70, v2
	v_mov_b32_e32 v71, v2
	v_mov_b32_e32 v72, v2
	v_mov_b32_e32 v73, v2
	v_mov_b32_e32 v82, v2
	v_mov_b32_e32 v83, v2
	v_mov_b32_e32 v84, v2
	v_mov_b32_e32 v85, v2
	v_mov_b32_e32 v86, v2
	v_mov_b32_e32 v87, v2
	v_mov_b32_e32 v88, v2
	v_mov_b32_e32 v89, v2
	v_mov_b32_e32 v98, v2
	v_mov_b32_e32 v99, v2
	v_mov_b32_e32 v100, v2
	v_mov_b32_e32 v101, v2
	v_mov_b32_e32 v102, v2
	v_mov_b32_e32 v103, v2
	v_mov_b32_e32 v104, v2
	v_mov_b32_e32 v105, v2
	v_mov_b32_e32 v114, v2
	v_mov_b32_e32 v115, v2
	v_mov_b32_e32 v116, v2
	v_mov_b32_e32 v117, v2
	v_mov_b32_e32 v118, v2
	v_mov_b32_e32 v119, v2
	v_mov_b32_e32 v120, v2
	v_mov_b32_e32 v121, v2
	v_mov_b32_e32 v74, v2
	v_mov_b32_e32 v75, v2
	v_mov_b32_e32 v76, v2
	v_mov_b32_e32 v77, v2
	v_mov_b32_e32 v78, v2
	v_mov_b32_e32 v79, v2
	v_mov_b32_e32 v80, v2
	v_mov_b32_e32 v81, v2
	v_mov_b32_e32 v90, v2
	v_mov_b32_e32 v91, v2
	v_mov_b32_e32 v92, v2
	v_mov_b32_e32 v93, v2
	v_mov_b32_e32 v94, v2
	v_mov_b32_e32 v95, v2
	v_mov_b32_e32 v96, v2
	v_mov_b32_e32 v97, v2
	v_mov_b32_e32 v106, v2
	v_mov_b32_e32 v107, v2
	v_mov_b32_e32 v108, v2
	v_mov_b32_e32 v109, v2
	v_mov_b32_e32 v110, v2
	v_mov_b32_e32 v111, v2
	v_mov_b32_e32 v112, v2
	v_mov_b32_e32 v113, v2
	v_mov_b32_e32 v122, v2
	v_mov_b32_e32 v123, v2
	v_mov_b32_e32 v124, v2
	v_mov_b32_e32 v125, v2
	v_mov_b32_e32 v126, v2
	v_mov_b32_e32 v127, v2
	v_mov_b32_e32 v128, v2
	v_mov_b32_e32 v129, v2
	s_and_b64 s[98:99], exec, s[10:11]
	s_cbranch_scc0 .Lsp_p6
	s_setprio 1

.LBB0_1219:
	s_and_b64 s[34:35], s[24:25], exec
	s_cselect_b32 s1, s21, s29
	s_cselect_b32 s17, s20, s28
	s_cselect_b32 s19, s23, s31
	s_cselect_b32 s48, s22, s30
	s_add_u32 s28, s28, 0x20080
	s_addc_u32 s29, s29, 0
	s_add_u32 s49, s30, 0x100
	v_mov_b32_e32 v2, 0
	s_addc_u32 s50, s31, 0
	s_mov_b32 s51, -2
	s_waitcnt lgkmcnt(0)
	v_mov_b32_e32 v3, v2
	v_mov_b32_e32 v4, v2
	v_mov_b32_e32 v5, v2
	v_mov_b32_e32 v6, v2
	v_mov_b32_e32 v7, v2
	v_mov_b32_e32 v8, v2
	v_mov_b32_e32 v9, v2
	v_mov_b32_e32 v18, v2
	v_mov_b32_e32 v19, v2
	v_mov_b32_e32 v20, v2
	v_mov_b32_e32 v21, v2
	v_mov_b32_e32 v22, v2
	v_mov_b32_e32 v23, v2
	v_mov_b32_e32 v24, v2
	v_mov_b32_e32 v25, v2
	v_mov_b32_e32 v34, v2
	v_mov_b32_e32 v35, v2
	v_mov_b32_e32 v36, v2
	v_mov_b32_e32 v37, v2
	v_mov_b32_e32 v38, v2
	v_mov_b32_e32 v39, v2
	v_mov_b32_e32 v40, v2
	v_mov_b32_e32 v41, v2
	v_mov_b32_e32 v50, v2
	v_mov_b32_e32 v51, v2
	v_mov_b32_e32 v52, v2
	v_mov_b32_e32 v53, v2
	v_mov_b32_e32 v54, v2
	v_mov_b32_e32 v55, v2
	v_mov_b32_e32 v56, v2
	v_mov_b32_e32 v57, v2
	v_mov_b32_e32 v10, v2
	v_mov_b32_e32 v11, v2
	v_mov_b32_e32 v12, v2
	v_mov_b32_e32 v13, v2
	v_mov_b32_e32 v14, v2
	v_mov_b32_e32 v15, v2
	v_mov_b32_e32 v16, v2
	v_mov_b32_e32 v17, v2
	v_mov_b32_e32 v26, v2
	v_mov_b32_e32 v27, v2
	v_mov_b32_e32 v28, v2
	v_mov_b32_e32 v29, v2
	v_mov_b32_e32 v30, v2
	v_mov_b32_e32 v31, v2
	v_mov_b32_e32 v32, v2
	v_mov_b32_e32 v33, v2
	v_mov_b32_e32 v42, v2
	v_mov_b32_e32 v43, v2
	v_mov_b32_e32 v44, v2
	v_mov_b32_e32 v45, v2
	v_mov_b32_e32 v46, v2
	v_mov_b32_e32 v47, v2
	v_mov_b32_e32 v48, v2
	v_mov_b32_e32 v49, v2
	v_mov_b32_e32 v58, v2
	v_mov_b32_e32 v59, v2
	v_mov_b32_e32 v60, v2
	v_mov_b32_e32 v61, v2
	v_mov_b32_e32 v62, v2
	v_mov_b32_e32 v63, v2
	v_mov_b32_e32 v64, v2
	v_mov_b32_e32 v65, v2
	v_mov_b32_e32 v66, v2
	v_mov_b32_e32 v67, v2
	v_mov_b32_e32 v68, v2
	v_mov_b32_e32 v69, v2
	v_mov_b32_e32 v70, v2
	v_mov_b32_e32 v71, v2
	v_mov_b32_e32 v72, v2
	v_mov_b32_e32 v73, v2
	v_mov_b32_e32 v82, v2
	v_mov_b32_e32 v83, v2
	v_mov_b32_e32 v84, v2
	v_mov_b32_e32 v85, v2
	v_mov_b32_e32 v86, v2
	v_mov_b32_e32 v87, v2
	v_mov_b32_e32 v88, v2
	v_mov_b32_e32 v89, v2
	v_mov_b32_e32 v98, v2
	v_mov_b32_e32 v99, v2
	v_mov_b32_e32 v100, v2
	v_mov_b32_e32 v101, v2
	v_mov_b32_e32 v102, v2
	v_mov_b32_e32 v103, v2
	v_mov_b32_e32 v104, v2
	v_mov_b32_e32 v105, v2
	v_mov_b32_e32 v114, v2
	v_mov_b32_e32 v115, v2
	v_mov_b32_e32 v116, v2
	v_mov_b32_e32 v117, v2
	v_mov_b32_e32 v118, v2
	v_mov_b32_e32 v119, v2
	v_mov_b32_e32 v120, v2
	v_mov_b32_e32 v121, v2
	v_mov_b32_e32 v74, v2
	v_mov_b32_e32 v75, v2
	v_mov_b32_e32 v76, v2
	v_mov_b32_e32 v77, v2
	v_mov_b32_e32 v78, v2
	v_mov_b32_e32 v79, v2
	v_mov_b32_e32 v80, v2
	v_mov_b32_e32 v81, v2
	v_mov_b32_e32 v90, v2
	v_mov_b32_e32 v91, v2
	v_mov_b32_e32 v92, v2
	v_mov_b32_e32 v93, v2
	v_mov_b32_e32 v94, v2
	v_mov_b32_e32 v95, v2
	v_mov_b32_e32 v96, v2
	v_mov_b32_e32 v97, v2
	v_mov_b32_e32 v106, v2
	v_mov_b32_e32 v107, v2
	v_mov_b32_e32 v108, v2
	v_mov_b32_e32 v109, v2
	v_mov_b32_e32 v110, v2
	v_mov_b32_e32 v111, v2
	v_mov_b32_e32 v112, v2
	v_mov_b32_e32 v113, v2
	v_mov_b32_e32 v122, v2
	v_mov_b32_e32 v123, v2
	v_mov_b32_e32 v124, v2
	v_mov_b32_e32 v125, v2
	v_mov_b32_e32 v126, v2
	v_mov_b32_e32 v127, v2
	v_mov_b32_e32 v128, v2
	v_mov_b32_e32 v129, v2
	s_and_b64 s[98:99], exec, s[12:13]
	s_cbranch_scc0 .Lsp_p9
	s_setprio 1

.LBB0_1336:
	s_and_b64 s[34:35], s[0:1], exec
	s_cselect_b32 s17, s21, s29
	s_cselect_b32 s19, s20, s28
	s_cselect_b32 s50, s23, s31
	s_cselect_b32 s51, s22, s30
	s_add_u32 s28, s28, 0x80080
	s_addc_u32 s29, s29, 0
	s_add_u32 s52, s30, 0x100
	v_mov_b32_e32 v6, 0
	s_addc_u32 s53, s31, 0
	s_mov_b32 s54, -2
	v_mov_b32_e32 v7, v6
	v_mov_b32_e32 v8, v6
	v_mov_b32_e32 v9, v6
	v_mov_b32_e32 v14, v6
	v_mov_b32_e32 v15, v6
	v_mov_b32_e32 v16, v6
	v_mov_b32_e32 v17, v6
	v_mov_b32_e32 v22, v6
	v_mov_b32_e32 v23, v6
	v_mov_b32_e32 v24, v6
	v_mov_b32_e32 v25, v6
	v_mov_b32_e32 v30, v6
	v_mov_b32_e32 v31, v6
	v_mov_b32_e32 v32, v6
	v_mov_b32_e32 v33, v6
	v_mov_b32_e32 v38, v6
	v_mov_b32_e32 v39, v6
	v_mov_b32_e32 v40, v6
	v_mov_b32_e32 v41, v6
	v_mov_b32_e32 v46, v6
	v_mov_b32_e32 v47, v6
	v_mov_b32_e32 v48, v6
	v_mov_b32_e32 v49, v6
	v_mov_b32_e32 v54, v6
	v_mov_b32_e32 v55, v6
	v_mov_b32_e32 v56, v6
	v_mov_b32_e32 v57, v6
	v_mov_b32_e32 v62, v6
	v_mov_b32_e32 v63, v6
	v_mov_b32_e32 v64, v6
	v_mov_b32_e32 v65, v6
	v_mov_b32_e32 v2, v6
	v_mov_b32_e32 v3, v6
	v_mov_b32_e32 v4, v6
	v_mov_b32_e32 v5, v6
	v_mov_b32_e32 v10, v6
	v_mov_b32_e32 v11, v6
	v_mov_b32_e32 v12, v6
	v_mov_b32_e32 v13, v6
	v_mov_b32_e32 v18, v6
	v_mov_b32_e32 v19, v6
	v_mov_b32_e32 v20, v6
	v_mov_b32_e32 v21, v6
	v_mov_b32_e32 v26, v6
	v_mov_b32_e32 v27, v6
	v_mov_b32_e32 v28, v6
	v_mov_b32_e32 v29, v6
	v_mov_b32_e32 v34, v6
	v_mov_b32_e32 v35, v6
	v_mov_b32_e32 v36, v6
	v_mov_b32_e32 v37, v6
	v_mov_b32_e32 v42, v6
	v_mov_b32_e32 v43, v6
	v_mov_b32_e32 v44, v6
	v_mov_b32_e32 v45, v6
	v_mov_b32_e32 v50, v6
	v_mov_b32_e32 v51, v6
	v_mov_b32_e32 v52, v6
	v_mov_b32_e32 v53, v6
	v_mov_b32_e32 v58, v6
	v_mov_b32_e32 v59, v6
	v_mov_b32_e32 v60, v6
	v_mov_b32_e32 v61, v6
	v_mov_b32_e32 v70, v6
	v_mov_b32_e32 v71, v6
	v_mov_b32_e32 v72, v6
	v_mov_b32_e32 v73, v6
	v_mov_b32_e32 v78, v6
	v_mov_b32_e32 v79, v6
	v_mov_b32_e32 v80, v6
	v_mov_b32_e32 v81, v6
	v_mov_b32_e32 v86, v6
	v_mov_b32_e32 v87, v6
	v_mov_b32_e32 v88, v6
	v_mov_b32_e32 v89, v6
	v_mov_b32_e32 v94, v6
	v_mov_b32_e32 v95, v6
	v_mov_b32_e32 v96, v6
	v_mov_b32_e32 v97, v6
	v_mov_b32_e32 v102, v6
	v_mov_b32_e32 v103, v6
	v_mov_b32_e32 v104, v6
	v_mov_b32_e32 v105, v6
	v_mov_b32_e32 v110, v6
	v_mov_b32_e32 v111, v6
	v_mov_b32_e32 v112, v6
	v_mov_b32_e32 v113, v6
	v_mov_b32_e32 v118, v6
	v_mov_b32_e32 v119, v6
	v_mov_b32_e32 v120, v6
	v_mov_b32_e32 v121, v6
	v_mov_b32_e32 v126, v6
	v_mov_b32_e32 v127, v6
	v_mov_b32_e32 v128, v6
	v_mov_b32_e32 v129, v6
	v_mov_b32_e32 v66, v6
	v_mov_b32_e32 v67, v6
	v_mov_b32_e32 v68, v6
	v_mov_b32_e32 v69, v6
	v_mov_b32_e32 v74, v6
	v_mov_b32_e32 v75, v6
	v_mov_b32_e32 v76, v6
	v_mov_b32_e32 v77, v6
	v_mov_b32_e32 v82, v6
	v_mov_b32_e32 v83, v6
	v_mov_b32_e32 v84, v6
	v_mov_b32_e32 v85, v6
	v_mov_b32_e32 v90, v6
	v_mov_b32_e32 v91, v6
	v_mov_b32_e32 v92, v6
	v_mov_b32_e32 v93, v6
	v_mov_b32_e32 v98, v6
	v_mov_b32_e32 v99, v6
	v_mov_b32_e32 v100, v6
	v_mov_b32_e32 v101, v6
	v_mov_b32_e32 v106, v6
	v_mov_b32_e32 v107, v6
	v_mov_b32_e32 v108, v6
	v_mov_b32_e32 v109, v6
	v_mov_b32_e32 v114, v6
	v_mov_b32_e32 v115, v6
	v_mov_b32_e32 v116, v6
	v_mov_b32_e32 v117, v6
	v_mov_b32_e32 v122, v6
	v_mov_b32_e32 v123, v6
	v_mov_b32_e32 v124, v6
	v_mov_b32_e32 v125, v6
	s_and_b64 vcc, exec, s[8:9]
	s_cbranch_vccnz .Lsp_p10
	s_setprio 1

.LBB0_1448:
	s_and_b64 s[22:23], s[18:19], exec
	s_cselect_b32 s25, s15, s1
	s_cselect_b32 s47, s14, s0
	s_cselect_b32 s48, s17, s21
	s_cselect_b32 s49, s16, s20
	s_add_u32 s0, s0, 0x160080
	s_addc_u32 s1, s1, 0
	s_add_u32 s50, s20, 0x100
	v_mov_b32_e32 v0, 0
	s_addc_u32 s51, s21, 0
	s_mov_b32 s52, -2
	v_mov_b32_e32 v1, v0
	v_mov_b32_e32 v2, v0
	v_mov_b32_e32 v3, v0
	v_mov_b32_e32 v4, v0
	v_mov_b32_e32 v5, v0
	v_mov_b32_e32 v6, v0
	v_mov_b32_e32 v7, v0
	v_mov_b32_e32 v16, v0
	v_mov_b32_e32 v17, v0
	v_mov_b32_e32 v18, v0
	v_mov_b32_e32 v19, v0
	v_mov_b32_e32 v20, v0
	v_mov_b32_e32 v21, v0
	v_mov_b32_e32 v22, v0
	v_mov_b32_e32 v23, v0
	v_mov_b32_e32 v32, v0
	v_mov_b32_e32 v33, v0
	v_mov_b32_e32 v34, v0
	v_mov_b32_e32 v35, v0
	v_mov_b32_e32 v36, v0
	v_mov_b32_e32 v37, v0
	v_mov_b32_e32 v38, v0
	v_mov_b32_e32 v39, v0
	v_mov_b32_e32 v48, v0
	v_mov_b32_e32 v49, v0
	v_mov_b32_e32 v50, v0
	v_mov_b32_e32 v51, v0
	v_mov_b32_e32 v52, v0
	v_mov_b32_e32 v53, v0
	v_mov_b32_e32 v54, v0
	v_mov_b32_e32 v55, v0
	v_mov_b32_e32 v8, v0
	v_mov_b32_e32 v9, v0
	v_mov_b32_e32 v10, v0
	v_mov_b32_e32 v11, v0
	v_mov_b32_e32 v12, v0
	v_mov_b32_e32 v13, v0
	v_mov_b32_e32 v14, v0
	v_mov_b32_e32 v15, v0
	v_mov_b32_e32 v24, v0
	v_mov_b32_e32 v25, v0
	v_mov_b32_e32 v26, v0
	v_mov_b32_e32 v27, v0
	v_mov_b32_e32 v28, v0
	v_mov_b32_e32 v29, v0
	v_mov_b32_e32 v30, v0
	v_mov_b32_e32 v31, v0
	v_mov_b32_e32 v40, v0
	v_mov_b32_e32 v41, v0
	v_mov_b32_e32 v42, v0
	v_mov_b32_e32 v43, v0
	v_mov_b32_e32 v44, v0
	v_mov_b32_e32 v45, v0
	v_mov_b32_e32 v46, v0
	v_mov_b32_e32 v47, v0
	v_mov_b32_e32 v56, v0
	v_mov_b32_e32 v57, v0
	v_mov_b32_e32 v58, v0
	v_mov_b32_e32 v59, v0
	v_mov_b32_e32 v60, v0
	v_mov_b32_e32 v61, v0
	v_mov_b32_e32 v62, v0
	v_mov_b32_e32 v63, v0
	v_mov_b32_e32 v64, v0
	v_mov_b32_e32 v65, v0
	v_mov_b32_e32 v66, v0
	v_mov_b32_e32 v67, v0
	v_mov_b32_e32 v68, v0
	v_mov_b32_e32 v69, v0
	v_mov_b32_e32 v70, v0
	v_mov_b32_e32 v71, v0
	v_mov_b32_e32 v80, v0
	v_mov_b32_e32 v81, v0
	v_mov_b32_e32 v82, v0
	v_mov_b32_e32 v83, v0
	v_mov_b32_e32 v84, v0
	v_mov_b32_e32 v85, v0
	v_mov_b32_e32 v86, v0
	v_mov_b32_e32 v87, v0
	v_mov_b32_e32 v96, v0
	v_mov_b32_e32 v97, v0
	v_mov_b32_e32 v98, v0
	v_mov_b32_e32 v99, v0
	v_mov_b32_e32 v100, v0
	v_mov_b32_e32 v101, v0
	v_mov_b32_e32 v102, v0
	v_mov_b32_e32 v103, v0
	v_mov_b32_e32 v112, v0
	v_mov_b32_e32 v113, v0
	v_mov_b32_e32 v114, v0
	v_mov_b32_e32 v115, v0
	v_mov_b32_e32 v116, v0
	v_mov_b32_e32 v117, v0
	v_mov_b32_e32 v118, v0
	v_mov_b32_e32 v119, v0
	v_mov_b32_e32 v72, v0
	v_mov_b32_e32 v73, v0
	v_mov_b32_e32 v74, v0
	v_mov_b32_e32 v75, v0
	v_mov_b32_e32 v76, v0
	v_mov_b32_e32 v77, v0
	v_mov_b32_e32 v78, v0
	v_mov_b32_e32 v79, v0
	v_mov_b32_e32 v88, v0
	v_mov_b32_e32 v89, v0
	v_mov_b32_e32 v90, v0
	v_mov_b32_e32 v91, v0
	v_mov_b32_e32 v92, v0
	v_mov_b32_e32 v93, v0
	v_mov_b32_e32 v94, v0
	v_mov_b32_e32 v95, v0
	v_mov_b32_e32 v104, v0
	v_mov_b32_e32 v105, v0
	v_mov_b32_e32 v106, v0
	v_mov_b32_e32 v107, v0
	v_mov_b32_e32 v108, v0
	v_mov_b32_e32 v109, v0
	v_mov_b32_e32 v110, v0
	v_mov_b32_e32 v111, v0
	v_mov_b32_e32 v120, v0
	v_mov_b32_e32 v121, v0
	v_mov_b32_e32 v122, v0
	v_mov_b32_e32 v123, v0
	v_mov_b32_e32 v124, v0
	v_mov_b32_e32 v125, v0
	v_mov_b32_e32 v126, v0
	v_mov_b32_e32 v127, v0
	s_and_b64 s[98:99], exec, s[10:11]
	s_cbranch_scc0 .Lsp_p11
	s_setprio 1
